# static s_setprio 1 for the younger wave half (waves 4-7) over the prompt attention loop (strategy 7.4)
# baseline (speedup 1.0000x reference)
.Latt_startB:
	s_setprio 1
	s_mov_b64 s[96:97], 0x13304000
	v_lshl_add_u64 v[246:247], v[172:173], 0, s[96:97]
	s_add_i32 m0, s84, 0xe000
	s_nop 0
	global_load_lds_dwordx4 v[246:247], off
	v_lshl_add_u64 v[246:247], v[174:175], 0, s[96:97]
	s_add_i32 m0, s84, 0xe400
	s_nop 0
	global_load_lds_dwordx4 v[246:247], off
	s_mov_b64 s[96:97], 0x4d802000
	v_lshl_add_u64 v[246:247], v[176:177], 0, s[96:97]
	s_add_i32 m0, s87, 0x12000
	s_nop 0
	global_load_lds_dwordx4 v[246:247], off
	s_barrier

.Latt_h5pB_skip:
	s_waitcnt vmcnt(0)
	s_waitcnt lgkmcnt(0)
	s_barrier
	s_setprio 0
	s_add_i32 s92, s19, 0
